# GEMM phase prologue: removed compiler-inserted vmcnt(0) between the first 8 and next 6 LDS-DMA tile loads (source protocol keeps its vmcnt(2)/vmcnt(6)), on top of static setprio + attention store tran
# speedup vs baseline: 1.0079x; 1.0079x over previous
; #define PG8_STAGE(bufoff, gbase, voff) do { _Pragma("unroll") for (int _i = 0; _i < 2; ++_i) \
;         __builtin_amdgcn_global_load_lds((const unsigned*)((const char*)(gbase) + (voff)[_i]), (PG8_LAS unsigned*)(lds + (bufoff) + ldsw + _i * 8192), 16, 0, 0); } while (0)
; #define PG8_WAIT_V(n) asm volatile("s_waitcnt vmcnt(" #n ")" ::: "memory")
; #define PG8_BAR __builtin_amdgcn_s_barrier()
; template <class Epi, class Sched, bool ALIGN_EPI = false, bool SP2 = false>
; __device__ __forceinline__ void gemm_phase(PG8_LAS unsigned char* lds, const Gemm g, const Sched& S, const Epi& E, const int tid_in) {
;     ...
;     for (int i = 0; i < 2; ++i) { int R, C; stage_rc(tid * 16 + i * 8192, R, C); const int Rb = Epi::PERM ? ((R & ~31) + perm32(R & 31)) : R;
;         voffA[i] = (unsigned)(R * K + C) * 2u; voffB[i] = (unsigned)(Rb * K + C) * 2u; }
;     ...
;     if constexpr (SP2) {
;         PG8_STAGE(PG8_SB(0, 0), cB, voffB); PG8_STAGE(PG8_SB(0, 1), cB + hstep, voffB); PG8_STAGE(PG8_SA(0, 0), cA, voffA); PG8_STAGE(PG8_SA(0, 1), cA + hstep, voffA);
;         if (wr == 1) PG8_BAR;
;         PG8_WAIT_V(2); PG8_BAR;
;         PG8_STAGE(PG8_SB(1, 0), cB + kstep, voffB); PG8_STAGE(PG8_SA(1, 0), cA + kstep, voffA); PG8_STAGE(PG8_SB(1, 1), cB + hstep + kstep, voffB);
;         PG8_WAIT_V(6); PG8_BAR;
.LBB0_126:
	s_andn2_b64 vcc, exec, s[0:1]
	s_cbranch_vccnz .LBB0_204
	v_bfe_i32 v3, v220, 27, 1
	v_lshlrev_b32_e32 v2, 4, v220
	v_lshrrev_b32_e32 v3, 22, v3
	v_add_u32_e32 v3, v2, v3
	v_and_b32_e32 v3, 0xfffffc00, v3
	v_sub_u32_e32 v3, v2, v3
	v_ashrrev_i32_e32 v0, 31, v220
	v_lshrrev_b32_e32 v4, 4, v3
	v_lshrrev_b32_e32 v0, 26, v0
	v_bitop3_b32 v3, v4, v3, 32 bitop3:0x6c
	v_add_u32_e32 v0, v220, v0
	v_ashrrev_i32_e32 v5, 31, v3
	v_ashrrev_i32_e32 v0, 6, v0
	v_lshrrev_b32_e32 v5, 26, v5
	v_lshlrev_b32_e32 v4, 3, v0
	v_add_u32_e32 v5, v3, v5
	v_and_b32_e32 v4, -16, v4
	s_waitcnt vmcnt(2)
	v_ashrrev_i32_e32 v6, 6, v5
	v_add_u32_e32 v4, v6, v4
	v_and_b32_e32 v5, 0xc0, v5
	v_sub_u32_e32 v3, v3, v5
	v_lshlrev_b32_e32 v5, 1, v4
	v_lshrrev_b32_e32 v7, 2, v4
	v_and_b32_e32 v6, 3, v6
	s_mov_b32 s0, 0x7fffffe0
	v_and_b32_e32 v5, 24, v5
	v_and_b32_e32 v7, 4, v7
	v_and_or_b32 v6, v4, s0, v6
	v_add_u32_e32 v2, 0x2000, v2
	v_or3_b32 v5, v6, v7, v5
	v_ashrrev_i32_e32 v6, 31, v2
	v_lshrrev_b32_e32 v6, 22, v6
	v_add_u32_e32 v6, v2, v6
	v_ashrrev_i32_e32 v6, 10, v6
	v_mul_i32_i24_e32 v7, 0x400, v6
	v_sub_u32_e32 v2, v2, v7
	v_lshrrev_b32_e32 v7, 4, v2
	v_bitop3_b32 v2, v7, v2, 32 bitop3:0x6c
	v_ashrrev_i32_e32 v8, 31, v2
	v_lshrrev_b32_e32 v8, 26, v8
	v_lshlrev_b32_e32 v7, 3, v6
	v_add_u32_e32 v8, v2, v8
	v_and_b32_e32 v7, -16, v7
	v_ashrrev_i32_e32 v9, 6, v8
	v_add_u32_e32 v7, v9, v7
	v_and_b32_e32 v9, 3, v9
	v_lshlrev_b32_e32 v6, 5, v6
	v_and_or_b32 v9, v7, s0, v9
	s_ashr_i32 s0, s15, 6
	s_lshl_b32 s56, s20, 9
	v_lshlrev_b32_e32 v0, 5, v0
	v_ashrrev_i16_sdwa v3, v214, sext(v3) dst_sel:DWORD dst_unused:UNUSED_PAD src0_sel:DWORD src1_sel:BYTE_0
	v_and_b32_e32 v15, 32, v6
	v_and_b32_e32 v6, 0xc0, v8
	s_ashr_i32 s1, s15, 8
	s_lshl_b32 s34, s20, 8
	s_lshl_b32 s57, s0, 10
	s_mul_i32 s17, s56, s55
	v_and_b32_e32 v0, 32, v0
	v_bfe_i32 v14, v3, 0, 16
	v_sub_u32_e32 v2, v2, v6
	v_lshlrev_b32_e32 v6, 1, v7
	v_lshrrev_b32_e32 v8, 2, v7
	s_mul_hi_i32 s16, s56, s55
	s_add_u32 s46, s6, s17
	v_add_u32_e32 v3, v0, v14
	v_ashrrev_i16_sdwa v2, v214, sext(v2) dst_sel:DWORD dst_unused:UNUSED_PAD src0_sel:DWORD src1_sel:BYTE_0
	v_and_b32_e32 v6, 24, v6
	v_and_b32_e32 v8, 4, v8
	v_mul_lo_u32 v18, s20, v4
	v_mul_lo_u32 v4, s20, v5
	s_addc_u32 s47, s7, s16
	s_add_i32 s58, s57, 0
	v_bfe_i32 v16, v2, 0, 16
	v_or3_b32 v6, v9, v8, v6
	v_add_lshl_u32 v198, v4, v3, 1
	s_add_i32 m0, s58, 0x10000
	v_add_u32_e32 v2, v15, v16
	v_add_lshl_u32 v196, v18, v3, 1
	v_mul_lo_u32 v3, s20, v6
	global_load_lds_dwordx4 v198, s[46:47]
	s_add_i32 m0, s58, 0x12000
	v_add_lshl_u32 v202, v3, v2, 1
	s_add_u32 s16, s46, s34
	global_load_lds_dwordx4 v202, s[46:47]
	s_addc_u32 s17, s47, 0
	s_add_i32 m0, s58, 0x14000
	s_mul_i32 s18, s56, s48
	global_load_lds_dwordx4 v198, s[16:17]
	s_add_i32 m0, s58, 0x16000
	s_mul_hi_i32 s11, s56, s48
	s_add_u32 s44, s12, s18
	v_mov_b32_e32 v199, v1
	v_mov_b32_e32 v203, v1
	s_addc_u32 s45, s13, s11
	s_add_i32 s59, s58, 0x2000
	v_mul_lo_u32 v17, s20, v7
	v_lshl_add_u64 v[6:7], s[16:17], 0, v[198:199]
	v_lshl_add_u64 v[8:9], s[16:17], 0, v[202:203]
	global_load_lds_dwordx4 v202, s[16:17]
	s_mov_b32 m0, s58
	s_add_u32 s16, s44, s34
	v_add_lshl_u32 v200, v17, v2, 1
	global_load_lds_dwordx4 v196, s[44:45]
	s_mov_b32 m0, s59
	s_addc_u32 s17, s45, 0
	s_add_i32 s60, s58, 0x4000
	global_load_lds_dwordx4 v200, s[44:45]
	s_mov_b32 m0, s60
	s_add_i32 s61, s58, 0x6000
	global_load_lds_dwordx4 v196, s[16:17]
	s_mov_b32 m0, s61
	v_mov_b32_e32 v197, v1
	global_load_lds_dwordx4 v200, s[16:17]
	v_mov_b32_e32 v201, v1
	s_cmp_eq_u32 s1, 1
	v_lshl_add_u64 v[2:3], s[46:47], 0, v[198:199]
	v_lshl_add_u64 v[4:5], s[46:47], 0, v[202:203]
	v_lshl_add_u64 v[10:11], s[44:45], 0, v[196:197]
	v_lshl_add_u64 v[12:13], s[44:45], 0, v[200:201]
	s_cselect_b64 s[16:17], -1, 0
	s_cmp_lg_u32 s1, 1
	s_cbranch_scc1 .LBB0_129
	s_barrier
